# SwiGLU epilogue algebra: out = g*u / (V*(1+2^(g*c1))) with V = mean-square+eps, c1 = -log2e*rsqrt(V); 2 fewer f32 multiplies per output, all f32
# speedup vs baseline: 1.0479x; 1.0122x over previous
; __device__ __forceinline__ float rs_from(const float* p, int n4, float inv_n) {
;     float s = 0.f;
;     for (int i = 0; i < n4; ++i) { const f32x4 v = *(const f32x4*)(p + 4 * i); s += (v[0] + v[1]) + (v[2] + v[3]); }
;     return rsqrtf(s * inv_n + EPS);
; }
;     __device__ __forceinline__ void operator()(AccRef acc, const pg8::Unit& u, int wr, int wc, int fr, int fq) const {
;         const int row0 = u.pm * 256 + wr * 64 + fr, col0 = u.pn * 128 + wc * 32 + 8 * fq;
; #pragma unroll
;         for (int ai = 0; ai < 2; ++ai)
; #pragma unroll
;             for (int m = 0; m < 4; ++m) {
;                 const int row = row0 + ai * 128 + m * 16;
;                 const float rs = rs_from(ssp + (size_t)row * 16, 4, 1.0f / 1024.0f);
;                 f32x4 o[2];
; #pragma unroll
;                 for (int n = 0; n < 2; ++n)
; #pragma unroll
;                     for (int j = 0; j < 4; ++j) {
;                         const float g = acc[ai][0][m][n][j] * rs, up = acc[ai][1][m][n][j] * rs;
;                         o[n][j] = g * __builtin_amdgcn_rcpf(1.0f + __expf(-g)) * up;
;                     }
;                 *(u32x4*)(act + (size_t)row * FF + col0) = pack8(o[0], o[1]);
.LBB0_376:
.Lswi_beg0:
	v_add_u32_e32 v249, 0x2000, v247
	global_load_dwordx4 v[154:157], v249, s[46:47]
	global_load_dwordx4 v[158:161], v249, s[46:47] offset:1024
	global_load_dwordx4 v[162:165], v249, s[46:47] offset:2048
	global_load_dwordx4 v[166:169], v249, s[46:47] offset:3072
	v_mbcnt_lo_u32_b32 v170, -1, 0
	v_mbcnt_hi_u32_b32 v170, -1, v170
	v_xor_b32_e32 v171, 16, v170
	v_xor_b32_e32 v172, 32, v170
	v_lshlrev_b32_e32 v171, 2, v171
	v_lshlrev_b32_e32 v172, 2, v172
	v_lshl_or_b32 v173, s61, 7, v148
	v_lshlrev_b32_e32 v173, 1, v173
	v_mad_u32_u24 v248, v246, s51, v173
	s_waitcnt vmcnt(12)
	v_add_f32_e32 v230, v230, v231
	v_add_f32_e32 v232, v232, v233
	v_add_f32_e32 v234, v234, v235
	v_add_f32_e32 v236, v236, v237
	v_add_f32_e32 v238, v238, v239
	v_add_f32_e32 v240, v240, v241
	v_add_f32_e32 v242, v242, v243
	v_add_f32_e32 v244, v244, v245
	v_add_f32_e32 v230, v230, v232
	v_add_f32_e32 v234, v234, v236
	v_add_f32_e32 v238, v238, v240
	v_add_f32_e32 v242, v242, v244
	ds_bpermute_b32 v231, v171, v230
	ds_bpermute_b32 v235, v171, v234
	ds_bpermute_b32 v239, v171, v238
	ds_bpermute_b32 v243, v171, v242
	s_waitcnt lgkmcnt(0)
	v_add_f32_e32 v230, v230, v231
	v_add_f32_e32 v234, v234, v235
	v_add_f32_e32 v238, v238, v239
	v_add_f32_e32 v242, v242, v243
	ds_bpermute_b32 v231, v172, v230
	ds_bpermute_b32 v235, v172, v234
	ds_bpermute_b32 v239, v172, v238
	ds_bpermute_b32 v243, v172, v242
	s_waitcnt lgkmcnt(0)
	v_add_f32_e32 v230, v230, v231
	v_add_f32_e32 v234, v234, v235
	v_add_f32_e32 v238, v238, v239
	v_add_f32_e32 v242, v242, v243
	v_fmamk_f32 v231, v230, 0x3a800000, v152
	v_fmamk_f32 v235, v234, 0x3a800000, v152
	v_fmamk_f32 v239, v238, 0x3a800000, v152
	v_fmamk_f32 v243, v242, 0x3a800000, v152
	v_rsq_f32_e32 v230, v231
	v_rsq_f32_e32 v234, v235
	v_rsq_f32_e32 v238, v239
	v_rsq_f32_e32 v242, v243
	s_nop 0
	v_mul_f32_e32 v230, 0xbfb8aa3b, v230
	v_mul_f32_e32 v234, 0xbfb8aa3b, v234
	v_mul_f32_e32 v238, 0xbfb8aa3b, v238
	v_mul_f32_e32 v242, 0xbfb8aa3b, v242
	v_mul_f32_e32 v176, v116, v230
	v_mul_f32_e32 v177, v117, v230
	v_mul_f32_e32 v178, v118, v230
	v_mul_f32_e32 v179, v119, v230
	v_mul_f32_e32 v180, v112, v230
	v_mul_f32_e32 v181, v113, v230
	v_mul_f32_e32 v182, v114, v230
	v_mul_f32_e32 v183, v115, v230
	v_exp_f32_e32 v176, v176
	v_exp_f32_e32 v177, v177
	v_exp_f32_e32 v178, v178
	v_exp_f32_e32 v179, v179
	v_exp_f32_e32 v180, v180
	v_exp_f32_e32 v181, v181
	v_exp_f32_e32 v182, v182
	v_exp_f32_e32 v183, v183
	v_fma_f32 v176, v176, v231, v231
	v_fma_f32 v177, v177, v231, v231
	v_fma_f32 v178, v178, v231, v231
	v_fma_f32 v179, v179, v231, v231
	v_fma_f32 v180, v180, v231, v231
	v_fma_f32 v181, v181, v231, v231
	v_fma_f32 v182, v182, v231, v231
	v_fma_f32 v183, v183, v231, v231
	v_rcp_f32_e32 v176, v176
	v_rcp_f32_e32 v177, v177
	v_rcp_f32_e32 v178, v178
	v_rcp_f32_e32 v179, v179
	v_rcp_f32_e32 v180, v180
	v_rcp_f32_e32 v181, v181
	v_rcp_f32_e32 v182, v182
	v_rcp_f32_e32 v183, v183
	v_pk_mul_f32 v[116:117], v[116:117], v[124:125]
	v_pk_mul_f32 v[118:119], v[118:119], v[126:127]
	v_pk_mul_f32 v[112:113], v[112:113], v[120:121]
	v_pk_mul_f32 v[114:115], v[114:115], v[122:123]
	v_pk_mul_f32 v[176:177], v[116:117], v[176:177]
	v_pk_mul_f32 v[178:179], v[118:119], v[178:179]
	v_pk_mul_f32 v[180:181], v[112:113], v[180:181]
	v_pk_mul_f32 v[182:183], v[114:115], v[182:183]
	v_cvt_pk_bf16_f32 v192, v176, v177
	v_cvt_pk_bf16_f32 v193, v178, v179
	v_cvt_pk_bf16_f32 v194, v180, v181
	v_cvt_pk_bf16_f32 v195, v182, v183
	v_mov_b32_e32 v200, v248
	global_store_dwordx4 v200, v[192:195], s[48:49] sc0 sc1
	v_mul_f32_e32 v184, v100, v234
	v_mul_f32_e32 v185, v101, v234
	v_mul_f32_e32 v186, v102, v234
	v_mul_f32_e32 v187, v103, v234
	v_mul_f32_e32 v188, v96, v234
	v_mul_f32_e32 v189, v97, v234
	v_mul_f32_e32 v190, v98, v234
	v_mul_f32_e32 v191, v99, v234
	v_exp_f32_e32 v184, v184
	v_exp_f32_e32 v185, v185
	v_exp_f32_e32 v186, v186
	v_exp_f32_e32 v187, v187
	v_exp_f32_e32 v188, v188
	v_exp_f32_e32 v189, v189
	v_exp_f32_e32 v190, v190
	v_exp_f32_e32 v191, v191
	v_fma_f32 v184, v184, v235, v235
	v_fma_f32 v185, v185, v235, v235
	v_fma_f32 v186, v186, v235, v235
	v_fma_f32 v187, v187, v235, v235
	v_fma_f32 v188, v188, v235, v235
	v_fma_f32 v189, v189, v235, v235
	v_fma_f32 v190, v190, v235, v235
	v_fma_f32 v191, v191, v235, v235
	v_rcp_f32_e32 v184, v184
	v_rcp_f32_e32 v185, v185
	v_rcp_f32_e32 v186, v186
	v_rcp_f32_e32 v187, v187
	v_rcp_f32_e32 v188, v188
	v_rcp_f32_e32 v189, v189
	v_rcp_f32_e32 v190, v190
	v_rcp_f32_e32 v191, v191
	v_pk_mul_f32 v[100:101], v[100:101], v[108:109]
	v_pk_mul_f32 v[102:103], v[102:103], v[110:111]
	v_pk_mul_f32 v[96:97], v[96:97], v[104:105]
	v_pk_mul_f32 v[98:99], v[98:99], v[106:107]
	v_pk_mul_f32 v[184:185], v[100:101], v[184:185]
	v_pk_mul_f32 v[186:187], v[102:103], v[186:187]
	v_pk_mul_f32 v[188:189], v[96:97], v[188:189]
	v_pk_mul_f32 v[190:191], v[98:99], v[190:191]
	v_cvt_pk_bf16_f32 v196, v184, v185
	v_cvt_pk_bf16_f32 v197, v186, v187
	v_cvt_pk_bf16_f32 v198, v188, v189
	v_cvt_pk_bf16_f32 v199, v190, v191
	v_add_u32_e32 v201, 0x16000, v248
	global_store_dwordx4 v201, v[196:199], s[48:49] sc0 sc1
	v_mul_f32_e32 v176, v84, v238
	v_mul_f32_e32 v177, v85, v238
	v_mul_f32_e32 v178, v86, v238
	v_mul_f32_e32 v179, v87, v238
	v_mul_f32_e32 v180, v80, v238
	v_mul_f32_e32 v181, v81, v238
	v_mul_f32_e32 v182, v82, v238
	v_mul_f32_e32 v183, v83, v238
	v_exp_f32_e32 v176, v176
	v_exp_f32_e32 v177, v177
	v_exp_f32_e32 v178, v178
	v_exp_f32_e32 v179, v179
	v_exp_f32_e32 v180, v180
	v_exp_f32_e32 v181, v181
	v_exp_f32_e32 v182, v182
	v_exp_f32_e32 v183, v183
	v_fma_f32 v176, v176, v239, v239
	v_fma_f32 v177, v177, v239, v239
;     __device__ __forceinline__ void operator()(AccRef acc, const pg8::Unit& u, int wr, int wc, int fr, int fq) const {
;         const int row0 = u.pm * 256 + wr * 64 + fr, col0 = u.pn * 128 + wc * 32 + 8 * fq;
; #pragma unroll
;         for (int ai = 0; ai < 2; ++ai)
; #pragma unroll
;             for (int m = 0; m < 4; ++m) {
;                 const int row = row0 + ai * 128 + m * 16;
;                 const float rs = rs_from(ssp + (size_t)row * 16, 4, 1.0f / 1024.0f);
;                 f32x4 o[2];
; #pragma unroll
;                 for (int n = 0; n < 2; ++n)
; #pragma unroll
;                     for (int j = 0; j < 4; ++j) {
;                         const float g = acc[ai][0][m][n][j] * rs, up = acc[ai][1][m][n][j] * rs;
;                         o[n][j] = g * __builtin_amdgcn_rcpf(1.0f + __expf(-g)) * up;
;                     }
;                 *(u32x4*)(act + (size_t)row * FF + col0) = pack8(o[0], o[1]);
	v_fma_f32 v178, v178, v239, v239
	v_fma_f32 v179, v179, v239, v239
	v_fma_f32 v180, v180, v239, v239
	v_fma_f32 v181, v181, v239, v239
	v_fma_f32 v182, v182, v239, v239
	v_fma_f32 v183, v183, v239, v239
	v_rcp_f32_e32 v176, v176
	v_rcp_f32_e32 v177, v177
	v_rcp_f32_e32 v178, v178
	v_rcp_f32_e32 v179, v179
	v_rcp_f32_e32 v180, v180
	v_rcp_f32_e32 v181, v181
	v_rcp_f32_e32 v182, v182
	v_rcp_f32_e32 v183, v183
	v_pk_mul_f32 v[84:85], v[84:85], v[92:93]
	v_pk_mul_f32 v[86:87], v[86:87], v[94:95]
	v_pk_mul_f32 v[80:81], v[80:81], v[88:89]
	v_pk_mul_f32 v[82:83], v[82:83], v[90:91]
	v_pk_mul_f32 v[176:177], v[84:85], v[176:177]
	v_pk_mul_f32 v[178:179], v[86:87], v[178:179]
	v_pk_mul_f32 v[180:181], v[80:81], v[180:181]
	v_pk_mul_f32 v[182:183], v[82:83], v[182:183]
	v_cvt_pk_bf16_f32 v192, v176, v177
	v_cvt_pk_bf16_f32 v193, v178, v179
	v_cvt_pk_bf16_f32 v194, v180, v181
	v_cvt_pk_bf16_f32 v195, v182, v183
	v_add_u32_e32 v200, 0x2c000, v248
	global_store_dwordx4 v200, v[192:195], s[48:49] sc0 sc1
	v_mul_f32_e32 v184, v68, v242
	v_mul_f32_e32 v185, v69, v242
	v_mul_f32_e32 v186, v70, v242
	v_mul_f32_e32 v187, v71, v242
	v_mul_f32_e32 v188, v64, v242
	v_mul_f32_e32 v189, v65, v242
	v_mul_f32_e32 v190, v66, v242
	v_mul_f32_e32 v191, v67, v242
	v_exp_f32_e32 v184, v184
	v_exp_f32_e32 v185, v185
	v_exp_f32_e32 v186, v186
	v_exp_f32_e32 v187, v187
	v_exp_f32_e32 v188, v188
	v_exp_f32_e32 v189, v189
	v_exp_f32_e32 v190, v190
	v_exp_f32_e32 v191, v191
	v_fma_f32 v184, v184, v243, v243
	v_fma_f32 v185, v185, v243, v243
	v_fma_f32 v186, v186, v243, v243
	v_fma_f32 v187, v187, v243, v243
	v_fma_f32 v188, v188, v243, v243
	v_fma_f32 v189, v189, v243, v243
	v_fma_f32 v190, v190, v243, v243
	v_fma_f32 v191, v191, v243, v243
	v_rcp_f32_e32 v184, v184
	v_rcp_f32_e32 v185, v185
	v_rcp_f32_e32 v186, v186
	v_rcp_f32_e32 v187, v187
	v_rcp_f32_e32 v188, v188
	v_rcp_f32_e32 v189, v189
	v_rcp_f32_e32 v190, v190
	v_rcp_f32_e32 v191, v191
	v_pk_mul_f32 v[68:69], v[68:69], v[76:77]
	v_pk_mul_f32 v[70:71], v[70:71], v[78:79]
	v_pk_mul_f32 v[64:65], v[64:65], v[72:73]
	v_pk_mul_f32 v[66:67], v[66:67], v[74:75]
	v_pk_mul_f32 v[184:185], v[68:69], v[184:185]
	v_pk_mul_f32 v[186:187], v[70:71], v[186:187]
	v_pk_mul_f32 v[188:189], v[64:65], v[188:189]
	v_pk_mul_f32 v[190:191], v[66:67], v[190:191]
	v_cvt_pk_bf16_f32 v196, v184, v185
	v_cvt_pk_bf16_f32 v197, v186, v187
	v_cvt_pk_bf16_f32 v198, v188, v189
	v_cvt_pk_bf16_f32 v199, v190, v191
	v_add_u32_e32 v201, 0x42000, v248
	global_store_dwordx4 v201, v[196:199], s[48:49] sc0 sc1
	s_waitcnt vmcnt(4)
	v_add_f32_e32 v154, v154, v155
	v_add_f32_e32 v156, v156, v157
	v_add_f32_e32 v158, v158, v159
	v_add_f32_e32 v160, v160, v161
	v_add_f32_e32 v162, v162, v163
	v_add_f32_e32 v164, v164, v165
	v_add_f32_e32 v166, v166, v167
	v_add_f32_e32 v168, v168, v169
	v_add_f32_e32 v154, v154, v156
	v_add_f32_e32 v158, v158, v160
	v_add_f32_e32 v162, v162, v164
	v_add_f32_e32 v166, v166, v168
	ds_bpermute_b32 v155, v171, v154
	ds_bpermute_b32 v159, v171, v158
	ds_bpermute_b32 v163, v171, v162
	ds_bpermute_b32 v167, v171, v166
	s_waitcnt lgkmcnt(0)
	v_add_f32_e32 v154, v154, v155
	v_add_f32_e32 v158, v158, v159
	v_add_f32_e32 v162, v162, v163
	v_add_f32_e32 v166, v166, v167
	ds_bpermute_b32 v155, v172, v154
	ds_bpermute_b32 v159, v172, v158
	ds_bpermute_b32 v163, v172, v162
	ds_bpermute_b32 v167, v172, v166
	s_waitcnt lgkmcnt(0)
; __device__ __forceinline__ float rs_from(const float* p, int n4, float inv_n) {
;     float s = 0.f;
;     for (int i = 0; i < n4; ++i) { const f32x4 v = *(const f32x4*)(p + 4 * i); s += (v[0] + v[1]) + (v[2] + v[3]); }
;     return rsqrtf(s * inv_n + EPS);
; }
;     __device__ __forceinline__ void operator()(AccRef acc, const pg8::Unit& u, int wr, int wc, int fr, int fq) const {
;         const int row0 = u.pm * 256 + wr * 64 + fr, col0 = u.pn * 128 + wc * 32 + 8 * fq;
; #pragma unroll
;         for (int ai = 0; ai < 2; ++ai)
; #pragma unroll
;             for (int m = 0; m < 4; ++m) {
;                 const int row = row0 + ai * 128 + m * 16;
;                 const float rs = rs_from(ssp + (size_t)row * 16, 4, 1.0f / 1024.0f);
;                 f32x4 o[2];
; #pragma unroll
;                 for (int n = 0; n < 2; ++n)
; #pragma unroll
;                     for (int j = 0; j < 4; ++j) {
;                         const float g = acc[ai][0][m][n][j] * rs, up = acc[ai][1][m][n][j] * rs;
;                         o[n][j] = g * __builtin_amdgcn_rcpf(1.0f + __expf(-g)) * up;
;                     }
;                 *(u32x4*)(act + (size_t)row * FF + col0) = pack8(o[0], o[1]);
	v_add_f32_e32 v154, v154, v155
	v_add_f32_e32 v158, v158, v159
	v_add_f32_e32 v162, v162, v163
	v_add_f32_e32 v166, v166, v167
	v_fmamk_f32 v155, v154, 0x3a800000, v152
	v_fmamk_f32 v159, v158, 0x3a800000, v152
	v_fmamk_f32 v163, v162, 0x3a800000, v152
	v_fmamk_f32 v167, v166, 0x3a800000, v152
	v_rsq_f32_e32 v154, v155
	v_rsq_f32_e32 v158, v159
	v_rsq_f32_e32 v162, v163
	v_rsq_f32_e32 v166, v167
	s_nop 0
	v_mul_f32_e32 v154, 0xbfb8aa3b, v154
	v_mul_f32_e32 v158, 0xbfb8aa3b, v158
	v_mul_f32_e32 v162, 0xbfb8aa3b, v162
	v_mul_f32_e32 v166, 0xbfb8aa3b, v166
	v_mul_f32_e32 v176, v52, v154
	v_mul_f32_e32 v177, v53, v154
	v_mul_f32_e32 v178, v54, v154
	v_mul_f32_e32 v179, v55, v154
	v_mul_f32_e32 v180, v48, v154
	v_mul_f32_e32 v181, v49, v154
	v_mul_f32_e32 v182, v50, v154
	v_mul_f32_e32 v183, v51, v154
	v_exp_f32_e32 v176, v176
	v_exp_f32_e32 v177, v177
	v_exp_f32_e32 v178, v178
	v_exp_f32_e32 v179, v179
	v_exp_f32_e32 v180, v180
	v_exp_f32_e32 v181, v181
	v_exp_f32_e32 v182, v182
	v_exp_f32_e32 v183, v183
	v_fma_f32 v176, v176, v155, v155
	v_fma_f32 v177, v177, v155, v155
	v_fma_f32 v178, v178, v155, v155
	v_fma_f32 v179, v179, v155, v155
	v_fma_f32 v180, v180, v155, v155
	v_fma_f32 v181, v181, v155, v155
	v_fma_f32 v182, v182, v155, v155
	v_fma_f32 v183, v183, v155, v155
	v_rcp_f32_e32 v176, v176
	v_rcp_f32_e32 v177, v177
	v_rcp_f32_e32 v178, v178
	v_rcp_f32_e32 v179, v179
	v_rcp_f32_e32 v180, v180
	v_rcp_f32_e32 v181, v181
	v_rcp_f32_e32 v182, v182
	v_rcp_f32_e32 v183, v183
	v_pk_mul_f32 v[52:53], v[52:53], v[60:61]
	v_pk_mul_f32 v[54:55], v[54:55], v[62:63]
	v_pk_mul_f32 v[48:49], v[48:49], v[56:57]
	v_pk_mul_f32 v[50:51], v[50:51], v[58:59]
	v_pk_mul_f32 v[176:177], v[52:53], v[176:177]
	v_pk_mul_f32 v[178:179], v[54:55], v[178:179]
	v_pk_mul_f32 v[180:181], v[48:49], v[180:181]
	v_pk_mul_f32 v[182:183], v[50:51], v[182:183]
	v_cvt_pk_bf16_f32 v192, v176, v177
	v_cvt_pk_bf16_f32 v193, v178, v179
	v_cvt_pk_bf16_f32 v194, v180, v181
	v_cvt_pk_bf16_f32 v195, v182, v183
	v_add_u32_e32 v200, 0xb0000, v248
	global_store_dwordx4 v200, v[192:195], s[48:49] sc0 sc1
	v_mul_f32_e32 v184, v36, v158
	v_mul_f32_e32 v185, v37, v158
	v_mul_f32_e32 v186, v38, v158
	v_mul_f32_e32 v187, v39, v158
	v_mul_f32_e32 v188, v32, v158
	v_mul_f32_e32 v189, v33, v158
	v_mul_f32_e32 v190, v34, v158
	v_mul_f32_e32 v191, v35, v158
	v_exp_f32_e32 v184, v184
	v_exp_f32_e32 v185, v185
	v_exp_f32_e32 v186, v186
	v_exp_f32_e32 v187, v187
	v_exp_f32_e32 v188, v188
	v_exp_f32_e32 v189, v189
	v_exp_f32_e32 v190, v190
	v_exp_f32_e32 v191, v191
	v_fma_f32 v184, v184, v159, v159
	v_fma_f32 v185, v185, v159, v159
	v_fma_f32 v186, v186, v159, v159
	v_fma_f32 v187, v187, v159, v159
	v_fma_f32 v188, v188, v159, v159
	v_fma_f32 v189, v189, v159, v159
	v_fma_f32 v190, v190, v159, v159
	v_fma_f32 v191, v191, v159, v159
	v_rcp_f32_e32 v184, v184
	v_rcp_f32_e32 v185, v185
	v_rcp_f32_e32 v186, v186
	v_rcp_f32_e32 v187, v187
	v_rcp_f32_e32 v188, v188
	v_rcp_f32_e32 v189, v189
	v_rcp_f32_e32 v190, v190
	v_rcp_f32_e32 v191, v191
	v_pk_mul_f32 v[36:37], v[36:37], v[44:45]
	v_pk_mul_f32 v[38:39], v[38:39], v[46:47]
	v_pk_mul_f32 v[32:33], v[32:33], v[40:41]
	v_pk_mul_f32 v[34:35], v[34:35], v[42:43]
	v_pk_mul_f32 v[184:185], v[36:37], v[184:185]
	v_pk_mul_f32 v[186:187], v[38:39], v[186:187]
	v_pk_mul_f32 v[188:189], v[32:33], v[188:189]
	v_pk_mul_f32 v[190:191], v[34:35], v[190:191]
	v_cvt_pk_bf16_f32 v196, v184, v185
	v_cvt_pk_bf16_f32 v197, v186, v187
	v_cvt_pk_bf16_f32 v198, v188, v189
	v_cvt_pk_bf16_f32 v199, v190, v191
	v_add_u32_e32 v201, 0xc6000, v248
	global_store_dwordx4 v201, v[196:199], s[48:49] sc0 sc1
	v_mul_f32_e32 v176, v20, v162
	v_mul_f32_e32 v177, v21, v162
	v_mul_f32_e32 v178, v22, v162
	v_mul_f32_e32 v179, v23, v162
	v_mul_f32_e32 v180, v16, v162
	v_mul_f32_e32 v181, v17, v162
	v_mul_f32_e32 v182, v18, v162
	v_mul_f32_e32 v183, v19, v162
	v_exp_f32_e32 v176, v176
	v_exp_f32_e32 v177, v177
	v_exp_f32_e32 v178, v178
	v_exp_f32_e32 v179, v179
	v_exp_f32_e32 v180, v180
	v_exp_f32_e32 v181, v181
	v_exp_f32_e32 v182, v182
	v_exp_f32_e32 v183, v183
	v_fma_f32 v176, v176, v163, v163
	v_fma_f32 v177, v177, v163, v163
	v_fma_f32 v178, v178, v163, v163
	v_fma_f32 v179, v179, v163, v163
	v_fma_f32 v180, v180, v163, v163
	v_fma_f32 v181, v181, v163, v163
	v_fma_f32 v182, v182, v163, v163
	v_fma_f32 v183, v183, v163, v163
	v_rcp_f32_e32 v176, v176
	v_rcp_f32_e32 v177, v177
	v_rcp_f32_e32 v178, v178
	v_rcp_f32_e32 v179, v179
	v_rcp_f32_e32 v180, v180
	v_rcp_f32_e32 v181, v181
	v_rcp_f32_e32 v182, v182
	v_rcp_f32_e32 v183, v183
	v_pk_mul_f32 v[20:21], v[20:21], v[28:29]
	v_pk_mul_f32 v[22:23], v[22:23], v[30:31]
	v_pk_mul_f32 v[16:17], v[16:17], v[24:25]
	v_pk_mul_f32 v[18:19], v[18:19], v[26:27]
	v_pk_mul_f32 v[176:177], v[20:21], v[176:177]
	v_pk_mul_f32 v[178:179], v[22:23], v[178:179]
	v_pk_mul_f32 v[180:181], v[16:17], v[180:181]
	v_pk_mul_f32 v[182:183], v[18:19], v[182:183]
	v_cvt_pk_bf16_f32 v192, v176, v177
	v_cvt_pk_bf16_f32 v193, v178, v179
	v_cvt_pk_bf16_f32 v194, v180, v181
	v_cvt_pk_bf16_f32 v195, v182, v183
	v_add_u32_e32 v200, 0xdc000, v248
	global_store_dwordx4 v200, v[192:195], s[48:49] sc0 sc1
	v_mul_f32_e32 v184, v4, v166
	v_mul_f32_e32 v185, v5, v166
	v_mul_f32_e32 v186, v6, v166
	v_mul_f32_e32 v187, v7, v166
	v_mul_f32_e32 v188, v0, v166
	v_mul_f32_e32 v189, v1, v166
	v_mul_f32_e32 v190, v2, v166
	v_mul_f32_e32 v191, v3, v166
	v_exp_f32_e32 v184, v184
	v_exp_f32_e32 v185, v185
	v_exp_f32_e32 v186, v186
	v_exp_f32_e32 v187, v187
	v_exp_f32_e32 v188, v188
	v_exp_f32_e32 v189, v189
	v_exp_f32_e32 v190, v190
	v_exp_f32_e32 v191, v191
	v_fma_f32 v184, v184, v167, v167
	v_fma_f32 v185, v185, v167, v167
	v_fma_f32 v186, v186, v167, v167
	v_fma_f32 v187, v187, v167, v167
	v_fma_f32 v188, v188, v167, v167
	v_fma_f32 v189, v189, v167, v167
	v_fma_f32 v190, v190, v167, v167
	v_fma_f32 v191, v191, v167, v167
	v_rcp_f32_e32 v184, v184
	v_rcp_f32_e32 v185, v185
	v_rcp_f32_e32 v186, v186
	v_rcp_f32_e32 v187, v187
	v_rcp_f32_e32 v188, v188
	v_rcp_f32_e32 v189, v189
	v_rcp_f32_e32 v190, v190
	v_rcp_f32_e32 v191, v191
	v_pk_mul_f32 v[4:5], v[4:5], v[12:13]
	v_pk_mul_f32 v[6:7], v[6:7], v[14:15]
	v_pk_mul_f32 v[0:1], v[0:1], v[8:9]
	v_pk_mul_f32 v[2:3], v[2:3], v[10:11]
	v_pk_mul_f32 v[184:185], v[4:5], v[184:185]
	v_pk_mul_f32 v[186:187], v[6:7], v[186:187]
	v_pk_mul_f32 v[188:189], v[0:1], v[188:189]
	v_pk_mul_f32 v[190:191], v[2:3], v[190:191]
	v_cvt_pk_bf16_f32 v196, v184, v185
	v_cvt_pk_bf16_f32 v197, v186, v187
	v_cvt_pk_bf16_f32 v198, v188, v189
	v_cvt_pk_bf16_f32 v199, v190, v191
	v_add_u32_e32 v201, 0xf2000, v248
	global_store_dwordx4 v201, v[196:199], s[48:49] sc0 sc1

; __device__ __forceinline__ float rs_from(const float* p, int n4, float inv_n) {
;     float s = 0.f;
;     for (int i = 0; i < n4; ++i) { const f32x4 v = *(const f32x4*)(p + 4 * i); s += (v[0] + v[1]) + (v[2] + v[3]); }
;     return rsqrtf(s * inv_n + EPS);
; }
;     __device__ __forceinline__ void operator()(AccRef acc, const pg8::Unit& u, int wr, int wc, int fr, int fq) const {
;         const int row0 = u.pm * 256 + wr * 64 + fr, col0 = u.pn * 128 + wc * 32 + 8 * fq;
; #pragma unroll
;         for (int ai = 0; ai < 2; ++ai)
; #pragma unroll
;             for (int m = 0; m < 4; ++m) {
;                 const int row = row0 + ai * 128 + m * 16;
;                 const float rs = rs_from(ssp + (size_t)row * 16, 4, 1.0f / 1024.0f);
;                 f32x4 o[2];
; #pragma unroll
;                 for (int n = 0; n < 2; ++n)
; #pragma unroll
;                     for (int j = 0; j < 4; ++j) {
;                         const float g = acc[ai][0][m][n][j] * rs, up = acc[ai][1][m][n][j] * rs;
;                         o[n][j] = g * __builtin_amdgcn_rcpf(1.0f + __expf(-g)) * up;
;                     }
;                 *(u32x4*)(act + (size_t)row * FF + col0) = pack8(o[0], o[1]);
.LBB0_1320:
.Lswi_beg1:
	v_add_u32_e32 v249, 0x2000, v247
	global_load_dwordx4 v[154:157], v249, s[46:47]
	global_load_dwordx4 v[158:161], v249, s[46:47] offset:1024
	global_load_dwordx4 v[162:165], v249, s[46:47] offset:2048
	global_load_dwordx4 v[166:169], v249, s[46:47] offset:3072
	v_mbcnt_lo_u32_b32 v170, -1, 0
	v_mbcnt_hi_u32_b32 v170, -1, v170
	v_xor_b32_e32 v171, 16, v170
	v_xor_b32_e32 v172, 32, v170
	v_lshlrev_b32_e32 v171, 2, v171
	v_lshlrev_b32_e32 v172, 2, v172
	v_lshl_or_b32 v173, s61, 7, v148
	v_lshlrev_b32_e32 v173, 1, v173
	v_mad_u32_u24 v248, v246, s57, v173
	s_waitcnt vmcnt(12)
	v_add_f32_e32 v230, v230, v231
	v_add_f32_e32 v232, v232, v233
	v_add_f32_e32 v234, v234, v235
	v_add_f32_e32 v236, v236, v237
	v_add_f32_e32 v238, v238, v239
	v_add_f32_e32 v240, v240, v241
	v_add_f32_e32 v242, v242, v243
	v_add_f32_e32 v244, v244, v245
	v_add_f32_e32 v230, v230, v232
	v_add_f32_e32 v234, v234, v236
	v_add_f32_e32 v238, v238, v240
	v_add_f32_e32 v242, v242, v244
	ds_bpermute_b32 v231, v171, v230
	ds_bpermute_b32 v235, v171, v234
	ds_bpermute_b32 v239, v171, v238
	ds_bpermute_b32 v243, v171, v242
	s_waitcnt lgkmcnt(0)
	v_add_f32_e32 v230, v230, v231
	v_add_f32_e32 v234, v234, v235
	v_add_f32_e32 v238, v238, v239
	v_add_f32_e32 v242, v242, v243
	ds_bpermute_b32 v231, v172, v230
	ds_bpermute_b32 v235, v172, v234
	ds_bpermute_b32 v239, v172, v238
	ds_bpermute_b32 v243, v172, v242
	s_waitcnt lgkmcnt(0)
	v_add_f32_e32 v230, v230, v231
	v_add_f32_e32 v234, v234, v235
	v_add_f32_e32 v238, v238, v239
	v_add_f32_e32 v242, v242, v243
	v_fmamk_f32 v231, v230, 0x3a800000, v152
	v_fmamk_f32 v235, v234, 0x3a800000, v152
	v_fmamk_f32 v239, v238, 0x3a800000, v152
	v_fmamk_f32 v243, v242, 0x3a800000, v152
	v_rsq_f32_e32 v230, v231
	v_rsq_f32_e32 v234, v235
	v_rsq_f32_e32 v238, v239
	v_rsq_f32_e32 v242, v243
	s_nop 0
	v_mul_f32_e32 v230, 0xbfb8aa3b, v230
	v_mul_f32_e32 v234, 0xbfb8aa3b, v234
	v_mul_f32_e32 v238, 0xbfb8aa3b, v238
	v_mul_f32_e32 v242, 0xbfb8aa3b, v242
	v_mul_f32_e32 v176, v116, v230
	v_mul_f32_e32 v177, v117, v230
	v_mul_f32_e32 v178, v118, v230
	v_mul_f32_e32 v179, v119, v230
	v_mul_f32_e32 v180, v112, v230
	v_mul_f32_e32 v181, v113, v230
	v_mul_f32_e32 v182, v114, v230
	v_mul_f32_e32 v183, v115, v230
	v_exp_f32_e32 v176, v176
	v_exp_f32_e32 v177, v177
	v_exp_f32_e32 v178, v178
	v_exp_f32_e32 v179, v179
	v_exp_f32_e32 v180, v180
	v_exp_f32_e32 v181, v181
	v_exp_f32_e32 v182, v182
	v_exp_f32_e32 v183, v183
	v_fma_f32 v176, v176, v231, v231
	v_fma_f32 v177, v177, v231, v231
	v_fma_f32 v178, v178, v231, v231
	v_fma_f32 v179, v179, v231, v231
	v_fma_f32 v180, v180, v231, v231
	v_fma_f32 v181, v181, v231, v231
	v_fma_f32 v182, v182, v231, v231
	v_fma_f32 v183, v183, v231, v231
	v_rcp_f32_e32 v176, v176
	v_rcp_f32_e32 v177, v177
	v_rcp_f32_e32 v178, v178
	v_rcp_f32_e32 v179, v179
	v_rcp_f32_e32 v180, v180
	v_rcp_f32_e32 v181, v181
	v_rcp_f32_e32 v182, v182
	v_rcp_f32_e32 v183, v183
	v_pk_mul_f32 v[116:117], v[116:117], v[124:125]
	v_pk_mul_f32 v[118:119], v[118:119], v[126:127]
	v_pk_mul_f32 v[112:113], v[112:113], v[120:121]
	v_pk_mul_f32 v[114:115], v[114:115], v[122:123]
	v_pk_mul_f32 v[176:177], v[116:117], v[176:177]
	v_pk_mul_f32 v[178:179], v[118:119], v[178:179]
	v_pk_mul_f32 v[180:181], v[112:113], v[180:181]
	v_pk_mul_f32 v[182:183], v[114:115], v[182:183]
	v_cvt_pk_bf16_f32 v192, v176, v177
	v_cvt_pk_bf16_f32 v193, v178, v179
	v_cvt_pk_bf16_f32 v194, v180, v181
	v_cvt_pk_bf16_f32 v195, v182, v183
	v_mov_b32_e32 v200, v248
	global_store_dwordx4 v200, v[192:195], s[48:49] sc0 sc1
	v_mul_f32_e32 v184, v100, v234
	v_mul_f32_e32 v185, v101, v234
	v_mul_f32_e32 v186, v102, v234
	v_mul_f32_e32 v187, v103, v234
	v_mul_f32_e32 v188, v96, v234
	v_mul_f32_e32 v189, v97, v234
	v_mul_f32_e32 v190, v98, v234
	v_mul_f32_e32 v191, v99, v234
	v_exp_f32_e32 v184, v184
	v_exp_f32_e32 v185, v185
	v_exp_f32_e32 v186, v186
	v_exp_f32_e32 v187, v187
	v_exp_f32_e32 v188, v188
	v_exp_f32_e32 v189, v189
	v_exp_f32_e32 v190, v190
	v_exp_f32_e32 v191, v191
	v_fma_f32 v184, v184, v235, v235
	v_fma_f32 v185, v185, v235, v235
	v_fma_f32 v186, v186, v235, v235
	v_fma_f32 v187, v187, v235, v235
	v_fma_f32 v188, v188, v235, v235
	v_fma_f32 v189, v189, v235, v235
	v_fma_f32 v190, v190, v235, v235
	v_fma_f32 v191, v191, v235, v235
	v_rcp_f32_e32 v184, v184
	v_rcp_f32_e32 v185, v185
	v_rcp_f32_e32 v186, v186
	v_rcp_f32_e32 v187, v187
	v_rcp_f32_e32 v188, v188
	v_rcp_f32_e32 v189, v189
	v_rcp_f32_e32 v190, v190
	v_rcp_f32_e32 v191, v191
	v_pk_mul_f32 v[100:101], v[100:101], v[108:109]
	v_pk_mul_f32 v[102:103], v[102:103], v[110:111]
	v_pk_mul_f32 v[96:97], v[96:97], v[104:105]
	v_pk_mul_f32 v[98:99], v[98:99], v[106:107]
	v_pk_mul_f32 v[184:185], v[100:101], v[184:185]
	v_pk_mul_f32 v[186:187], v[102:103], v[186:187]
	v_pk_mul_f32 v[188:189], v[96:97], v[188:189]
	v_pk_mul_f32 v[190:191], v[98:99], v[190:191]
	v_cvt_pk_bf16_f32 v196, v184, v185
	v_cvt_pk_bf16_f32 v197, v186, v187
	v_cvt_pk_bf16_f32 v198, v188, v189
	v_cvt_pk_bf16_f32 v199, v190, v191
	v_add_u32_e32 v201, 0x16000, v248
	global_store_dwordx4 v201, v[196:199], s[48:49] sc0 sc1
	v_mul_f32_e32 v176, v84, v238
	v_mul_f32_e32 v177, v85, v238
	v_mul_f32_e32 v178, v86, v238
	v_mul_f32_e32 v179, v87, v238
	v_mul_f32_e32 v180, v80, v238
	v_mul_f32_e32 v181, v81, v238
	v_mul_f32_e32 v182, v82, v238
	v_mul_f32_e32 v183, v83, v238
	v_exp_f32_e32 v176, v176
	v_exp_f32_e32 v177, v177
	v_exp_f32_e32 v178, v178
	v_exp_f32_e32 v179, v179
	v_exp_f32_e32 v180, v180
	v_exp_f32_e32 v181, v181
	v_exp_f32_e32 v182, v182
	v_exp_f32_e32 v183, v183
	v_fma_f32 v176, v176, v239, v239
	v_fma_f32 v177, v177, v239, v239
;     __device__ __forceinline__ void operator()(AccRef acc, const pg8::Unit& u, int wr, int wc, int fr, int fq) const {
;         const int row0 = u.pm * 256 + wr * 64 + fr, col0 = u.pn * 128 + wc * 32 + 8 * fq;
; #pragma unroll
;         for (int ai = 0; ai < 2; ++ai)
; #pragma unroll
;             for (int m = 0; m < 4; ++m) {
;                 const int row = row0 + ai * 128 + m * 16;
;                 const float rs = rs_from(ssp + (size_t)row * 16, 4, 1.0f / 1024.0f);
;                 f32x4 o[2];
; #pragma unroll
;                 for (int n = 0; n < 2; ++n)
; #pragma unroll
;                     for (int j = 0; j < 4; ++j) {
;                         const float g = acc[ai][0][m][n][j] * rs, up = acc[ai][1][m][n][j] * rs;
;                         o[n][j] = g * __builtin_amdgcn_rcpf(1.0f + __expf(-g)) * up;
;                     }
;                 *(u32x4*)(act + (size_t)row * FF + col0) = pack8(o[0], o[1]);
	v_fma_f32 v178, v178, v239, v239
	v_fma_f32 v179, v179, v239, v239
	v_fma_f32 v180, v180, v239, v239
	v_fma_f32 v181, v181, v239, v239
	v_fma_f32 v182, v182, v239, v239
	v_fma_f32 v183, v183, v239, v239
	v_rcp_f32_e32 v176, v176
	v_rcp_f32_e32 v177, v177
	v_rcp_f32_e32 v178, v178
	v_rcp_f32_e32 v179, v179
	v_rcp_f32_e32 v180, v180
	v_rcp_f32_e32 v181, v181
	v_rcp_f32_e32 v182, v182
	v_rcp_f32_e32 v183, v183
	v_pk_mul_f32 v[84:85], v[84:85], v[92:93]
	v_pk_mul_f32 v[86:87], v[86:87], v[94:95]
	v_pk_mul_f32 v[80:81], v[80:81], v[88:89]
	v_pk_mul_f32 v[82:83], v[82:83], v[90:91]
	v_pk_mul_f32 v[176:177], v[84:85], v[176:177]
	v_pk_mul_f32 v[178:179], v[86:87], v[178:179]
	v_pk_mul_f32 v[180:181], v[80:81], v[180:181]
	v_pk_mul_f32 v[182:183], v[82:83], v[182:183]
	v_cvt_pk_bf16_f32 v192, v176, v177
	v_cvt_pk_bf16_f32 v193, v178, v179
	v_cvt_pk_bf16_f32 v194, v180, v181
	v_cvt_pk_bf16_f32 v195, v182, v183
	v_add_u32_e32 v200, 0x2c000, v248
	global_store_dwordx4 v200, v[192:195], s[48:49] sc0 sc1
	v_mul_f32_e32 v184, v68, v242
	v_mul_f32_e32 v185, v69, v242
	v_mul_f32_e32 v186, v70, v242
	v_mul_f32_e32 v187, v71, v242
	v_mul_f32_e32 v188, v64, v242
	v_mul_f32_e32 v189, v65, v242
	v_mul_f32_e32 v190, v66, v242
	v_mul_f32_e32 v191, v67, v242
	v_exp_f32_e32 v184, v184
	v_exp_f32_e32 v185, v185
	v_exp_f32_e32 v186, v186
	v_exp_f32_e32 v187, v187
	v_exp_f32_e32 v188, v188
	v_exp_f32_e32 v189, v189
	v_exp_f32_e32 v190, v190
	v_exp_f32_e32 v191, v191
	v_fma_f32 v184, v184, v243, v243
	v_fma_f32 v185, v185, v243, v243
	v_fma_f32 v186, v186, v243, v243
	v_fma_f32 v187, v187, v243, v243
	v_fma_f32 v188, v188, v243, v243
	v_fma_f32 v189, v189, v243, v243
	v_fma_f32 v190, v190, v243, v243
	v_fma_f32 v191, v191, v243, v243
	v_rcp_f32_e32 v184, v184
	v_rcp_f32_e32 v185, v185
	v_rcp_f32_e32 v186, v186
	v_rcp_f32_e32 v187, v187
	v_rcp_f32_e32 v188, v188
	v_rcp_f32_e32 v189, v189
	v_rcp_f32_e32 v190, v190
	v_rcp_f32_e32 v191, v191
	v_pk_mul_f32 v[68:69], v[68:69], v[76:77]
	v_pk_mul_f32 v[70:71], v[70:71], v[78:79]
	v_pk_mul_f32 v[64:65], v[64:65], v[72:73]
	v_pk_mul_f32 v[66:67], v[66:67], v[74:75]
	v_pk_mul_f32 v[184:185], v[68:69], v[184:185]
	v_pk_mul_f32 v[186:187], v[70:71], v[186:187]
	v_pk_mul_f32 v[188:189], v[64:65], v[188:189]
	v_pk_mul_f32 v[190:191], v[66:67], v[190:191]
	v_cvt_pk_bf16_f32 v196, v184, v185
	v_cvt_pk_bf16_f32 v197, v186, v187
	v_cvt_pk_bf16_f32 v198, v188, v189
	v_cvt_pk_bf16_f32 v199, v190, v191
	v_add_u32_e32 v201, 0x42000, v248
	global_store_dwordx4 v201, v[196:199], s[48:49] sc0 sc1
	s_waitcnt vmcnt(4)
	v_add_f32_e32 v154, v154, v155
	v_add_f32_e32 v156, v156, v157
	v_add_f32_e32 v158, v158, v159
	v_add_f32_e32 v160, v160, v161
	v_add_f32_e32 v162, v162, v163
	v_add_f32_e32 v164, v164, v165
	v_add_f32_e32 v166, v166, v167
	v_add_f32_e32 v168, v168, v169
	v_add_f32_e32 v154, v154, v156
	v_add_f32_e32 v158, v158, v160
	v_add_f32_e32 v162, v162, v164
	v_add_f32_e32 v166, v166, v168
	ds_bpermute_b32 v155, v171, v154
	ds_bpermute_b32 v159, v171, v158
	ds_bpermute_b32 v163, v171, v162
	ds_bpermute_b32 v167, v171, v166
	s_waitcnt lgkmcnt(0)
	v_add_f32_e32 v154, v154, v155
	v_add_f32_e32 v158, v158, v159
	v_add_f32_e32 v162, v162, v163
	v_add_f32_e32 v166, v166, v167
	ds_bpermute_b32 v155, v172, v154
	ds_bpermute_b32 v159, v172, v158
	ds_bpermute_b32 v163, v172, v162
	ds_bpermute_b32 v167, v172, v166
	s_waitcnt lgkmcnt(0)
; __device__ __forceinline__ float rs_from(const float* p, int n4, float inv_n) {
;     float s = 0.f;
;     for (int i = 0; i < n4; ++i) { const f32x4 v = *(const f32x4*)(p + 4 * i); s += (v[0] + v[1]) + (v[2] + v[3]); }
;     return rsqrtf(s * inv_n + EPS);
; }
;     __device__ __forceinline__ void operator()(AccRef acc, const pg8::Unit& u, int wr, int wc, int fr, int fq) const {
;         const int row0 = u.pm * 256 + wr * 64 + fr, col0 = u.pn * 128 + wc * 32 + 8 * fq;
; #pragma unroll
;         for (int ai = 0; ai < 2; ++ai)
; #pragma unroll
;             for (int m = 0; m < 4; ++m) {
;                 const int row = row0 + ai * 128 + m * 16;
;                 const float rs = rs_from(ssp + (size_t)row * 16, 4, 1.0f / 1024.0f);
;                 f32x4 o[2];
; #pragma unroll
;                 for (int n = 0; n < 2; ++n)
; #pragma unroll
;                     for (int j = 0; j < 4; ++j) {
;                         const float g = acc[ai][0][m][n][j] * rs, up = acc[ai][1][m][n][j] * rs;
;                         o[n][j] = g * __builtin_amdgcn_rcpf(1.0f + __expf(-g)) * up;
;                     }
;                 *(u32x4*)(act + (size_t)row * FF + col0) = pack8(o[0], o[1]);
	v_add_f32_e32 v154, v154, v155
	v_add_f32_e32 v158, v158, v159
	v_add_f32_e32 v162, v162, v163
	v_add_f32_e32 v166, v166, v167
	v_fmamk_f32 v155, v154, 0x3a800000, v152
	v_fmamk_f32 v159, v158, 0x3a800000, v152
	v_fmamk_f32 v163, v162, 0x3a800000, v152
	v_fmamk_f32 v167, v166, 0x3a800000, v152
	v_rsq_f32_e32 v154, v155
	v_rsq_f32_e32 v158, v159
	v_rsq_f32_e32 v162, v163
	v_rsq_f32_e32 v166, v167
	s_nop 0
	v_mul_f32_e32 v154, 0xbfb8aa3b, v154
	v_mul_f32_e32 v158, 0xbfb8aa3b, v158
	v_mul_f32_e32 v162, 0xbfb8aa3b, v162
	v_mul_f32_e32 v166, 0xbfb8aa3b, v166
	v_mul_f32_e32 v176, v52, v154
	v_mul_f32_e32 v177, v53, v154
	v_mul_f32_e32 v178, v54, v154
	v_mul_f32_e32 v179, v55, v154
	v_mul_f32_e32 v180, v48, v154
	v_mul_f32_e32 v181, v49, v154
	v_mul_f32_e32 v182, v50, v154
	v_mul_f32_e32 v183, v51, v154
	v_exp_f32_e32 v176, v176
	v_exp_f32_e32 v177, v177
	v_exp_f32_e32 v178, v178
	v_exp_f32_e32 v179, v179
	v_exp_f32_e32 v180, v180
	v_exp_f32_e32 v181, v181
	v_exp_f32_e32 v182, v182
	v_exp_f32_e32 v183, v183
	v_fma_f32 v176, v176, v155, v155
	v_fma_f32 v177, v177, v155, v155
	v_fma_f32 v178, v178, v155, v155
	v_fma_f32 v179, v179, v155, v155
	v_fma_f32 v180, v180, v155, v155
	v_fma_f32 v181, v181, v155, v155
	v_fma_f32 v182, v182, v155, v155
	v_fma_f32 v183, v183, v155, v155
	v_rcp_f32_e32 v176, v176
	v_rcp_f32_e32 v177, v177
	v_rcp_f32_e32 v178, v178
	v_rcp_f32_e32 v179, v179
	v_rcp_f32_e32 v180, v180
	v_rcp_f32_e32 v181, v181
	v_rcp_f32_e32 v182, v182
	v_rcp_f32_e32 v183, v183
	v_pk_mul_f32 v[52:53], v[52:53], v[60:61]
	v_pk_mul_f32 v[54:55], v[54:55], v[62:63]
	v_pk_mul_f32 v[48:49], v[48:49], v[56:57]
	v_pk_mul_f32 v[50:51], v[50:51], v[58:59]
	v_pk_mul_f32 v[176:177], v[52:53], v[176:177]
	v_pk_mul_f32 v[178:179], v[54:55], v[178:179]
	v_pk_mul_f32 v[180:181], v[48:49], v[180:181]
	v_pk_mul_f32 v[182:183], v[50:51], v[182:183]
	v_cvt_pk_bf16_f32 v192, v176, v177
	v_cvt_pk_bf16_f32 v193, v178, v179
	v_cvt_pk_bf16_f32 v194, v180, v181
	v_cvt_pk_bf16_f32 v195, v182, v183
	v_add_u32_e32 v200, 0xb0000, v248
	global_store_dwordx4 v200, v[192:195], s[48:49] sc0 sc1
	v_mul_f32_e32 v184, v36, v158
	v_mul_f32_e32 v185, v37, v158
	v_mul_f32_e32 v186, v38, v158
	v_mul_f32_e32 v187, v39, v158
	v_mul_f32_e32 v188, v32, v158
	v_mul_f32_e32 v189, v33, v158
	v_mul_f32_e32 v190, v34, v158
	v_mul_f32_e32 v191, v35, v158
	v_exp_f32_e32 v184, v184
	v_exp_f32_e32 v185, v185
	v_exp_f32_e32 v186, v186
	v_exp_f32_e32 v187, v187
	v_exp_f32_e32 v188, v188
	v_exp_f32_e32 v189, v189
	v_exp_f32_e32 v190, v190
	v_exp_f32_e32 v191, v191
	v_fma_f32 v184, v184, v159, v159
	v_fma_f32 v185, v185, v159, v159
	v_fma_f32 v186, v186, v159, v159
	v_fma_f32 v187, v187, v159, v159
	v_fma_f32 v188, v188, v159, v159
	v_fma_f32 v189, v189, v159, v159
	v_fma_f32 v190, v190, v159, v159
	v_fma_f32 v191, v191, v159, v159
	v_rcp_f32_e32 v184, v184
	v_rcp_f32_e32 v185, v185
	v_rcp_f32_e32 v186, v186
	v_rcp_f32_e32 v187, v187
	v_rcp_f32_e32 v188, v188
	v_rcp_f32_e32 v189, v189
	v_rcp_f32_e32 v190, v190
	v_rcp_f32_e32 v191, v191
	v_pk_mul_f32 v[36:37], v[36:37], v[44:45]
	v_pk_mul_f32 v[38:39], v[38:39], v[46:47]
	v_pk_mul_f32 v[32:33], v[32:33], v[40:41]
	v_pk_mul_f32 v[34:35], v[34:35], v[42:43]
	v_pk_mul_f32 v[184:185], v[36:37], v[184:185]
	v_pk_mul_f32 v[186:187], v[38:39], v[186:187]
	v_pk_mul_f32 v[188:189], v[32:33], v[188:189]
	v_pk_mul_f32 v[190:191], v[34:35], v[190:191]
	v_cvt_pk_bf16_f32 v196, v184, v185
	v_cvt_pk_bf16_f32 v197, v186, v187
	v_cvt_pk_bf16_f32 v198, v188, v189
	v_cvt_pk_bf16_f32 v199, v190, v191
	v_add_u32_e32 v201, 0xc6000, v248
	global_store_dwordx4 v201, v[196:199], s[48:49] sc0 sc1
	v_mul_f32_e32 v176, v20, v162
	v_mul_f32_e32 v177, v21, v162
	v_mul_f32_e32 v178, v22, v162
	v_mul_f32_e32 v179, v23, v162
	v_mul_f32_e32 v180, v16, v162
	v_mul_f32_e32 v181, v17, v162
	v_mul_f32_e32 v182, v18, v162
	v_mul_f32_e32 v183, v19, v162
	v_exp_f32_e32 v176, v176
	v_exp_f32_e32 v177, v177
	v_exp_f32_e32 v178, v178
	v_exp_f32_e32 v179, v179
	v_exp_f32_e32 v180, v180
	v_exp_f32_e32 v181, v181
	v_exp_f32_e32 v182, v182
	v_exp_f32_e32 v183, v183
	v_fma_f32 v176, v176, v163, v163
	v_fma_f32 v177, v177, v163, v163
	v_fma_f32 v178, v178, v163, v163
	v_fma_f32 v179, v179, v163, v163
	v_fma_f32 v180, v180, v163, v163
	v_fma_f32 v181, v181, v163, v163
	v_fma_f32 v182, v182, v163, v163
	v_fma_f32 v183, v183, v163, v163
	v_rcp_f32_e32 v176, v176
	v_rcp_f32_e32 v177, v177
	v_rcp_f32_e32 v178, v178
	v_rcp_f32_e32 v179, v179
	v_rcp_f32_e32 v180, v180
	v_rcp_f32_e32 v181, v181
	v_rcp_f32_e32 v182, v182
	v_rcp_f32_e32 v183, v183
	v_pk_mul_f32 v[20:21], v[20:21], v[28:29]
	v_pk_mul_f32 v[22:23], v[22:23], v[30:31]
	v_pk_mul_f32 v[16:17], v[16:17], v[24:25]
	v_pk_mul_f32 v[18:19], v[18:19], v[26:27]
	v_pk_mul_f32 v[176:177], v[20:21], v[176:177]
	v_pk_mul_f32 v[178:179], v[22:23], v[178:179]
	v_pk_mul_f32 v[180:181], v[16:17], v[180:181]
	v_pk_mul_f32 v[182:183], v[18:19], v[182:183]
	v_cvt_pk_bf16_f32 v192, v176, v177
	v_cvt_pk_bf16_f32 v193, v178, v179
	v_cvt_pk_bf16_f32 v194, v180, v181
	v_cvt_pk_bf16_f32 v195, v182, v183
	v_add_u32_e32 v200, 0xdc000, v248
	global_store_dwordx4 v200, v[192:195], s[48:49] sc0 sc1
	v_mul_f32_e32 v184, v4, v166
	v_mul_f32_e32 v185, v5, v166
	v_mul_f32_e32 v186, v6, v166
	v_mul_f32_e32 v187, v7, v166
	v_mul_f32_e32 v188, v0, v166
	v_mul_f32_e32 v189, v1, v166
	v_mul_f32_e32 v190, v2, v166
	v_mul_f32_e32 v191, v3, v166
	v_exp_f32_e32 v184, v184
	v_exp_f32_e32 v185, v185
	v_exp_f32_e32 v186, v186
	v_exp_f32_e32 v187, v187
	v_exp_f32_e32 v188, v188
	v_exp_f32_e32 v189, v189
	v_exp_f32_e32 v190, v190
	v_exp_f32_e32 v191, v191
	v_fma_f32 v184, v184, v167, v167
	v_fma_f32 v185, v185, v167, v167
	v_fma_f32 v186, v186, v167, v167
	v_fma_f32 v187, v187, v167, v167
	v_fma_f32 v188, v188, v167, v167
	v_fma_f32 v189, v189, v167, v167
	v_fma_f32 v190, v190, v167, v167
	v_fma_f32 v191, v191, v167, v167
	v_rcp_f32_e32 v184, v184
	v_rcp_f32_e32 v185, v185
	v_rcp_f32_e32 v186, v186
	v_rcp_f32_e32 v187, v187
	v_rcp_f32_e32 v188, v188
	v_rcp_f32_e32 v189, v189
	v_rcp_f32_e32 v190, v190
	v_rcp_f32_e32 v191, v191
	v_pk_mul_f32 v[4:5], v[4:5], v[12:13]
	v_pk_mul_f32 v[6:7], v[6:7], v[14:15]
	v_pk_mul_f32 v[0:1], v[0:1], v[8:9]
	v_pk_mul_f32 v[2:3], v[2:3], v[10:11]
	v_pk_mul_f32 v[184:185], v[4:5], v[184:185]
	v_pk_mul_f32 v[186:187], v[6:7], v[186:187]
	v_pk_mul_f32 v[188:189], v[0:1], v[188:189]
	v_pk_mul_f32 v[190:191], v[2:3], v[190:191]
	v_cvt_pk_bf16_f32 v196, v184, v185
	v_cvt_pk_bf16_f32 v197, v186, v187
	v_cvt_pk_bf16_f32 v198, v188, v189
	v_cvt_pk_bf16_f32 v199, v190, v191
	v_add_u32_e32 v201, 0xf2000, v248
	global_store_dwordx4 v201, v[196:199], s[48:49] sc0 sc1

; __device__ __forceinline__ float rs_from(const float* p, int n4, float inv_n) {
;     float s = 0.f;
;     for (int i = 0; i < n4; ++i) { const f32x4 v = *(const f32x4*)(p + 4 * i); s += (v[0] + v[1]) + (v[2] + v[3]); }
;     return rsqrtf(s * inv_n + EPS);
; }
;     __device__ __forceinline__ void operator()(AccRef acc, const pg8::Unit& u, int wr, int wc, int fr, int fq) const {
;         const int row0 = u.pm * 256 + wr * 64 + fr, col0 = u.pn * 128 + wc * 32 + 8 * fq;
; #pragma unroll
;         for (int ai = 0; ai < 2; ++ai)
; #pragma unroll
;             for (int m = 0; m < 4; ++m) {
;                 const int row = row0 + ai * 128 + m * 16;
;                 const float rs = rs_from(ssp + (size_t)row * 16, 4, 1.0f / 1024.0f);
;                 f32x4 o[2];
; #pragma unroll
;                 for (int n = 0; n < 2; ++n)
; #pragma unroll
;                     for (int j = 0; j < 4; ++j) {
;                         const float g = acc[ai][0][m][n][j] * rs, up = acc[ai][1][m][n][j] * rs;
;                         o[n][j] = g * __builtin_amdgcn_rcpf(1.0f + __expf(-g)) * up;
;                     }
;                 *(u32x4*)(act + (size_t)row * FF + col0) = pack8(o[0], o[1]);
.LBB0_2484:
.Lswi_beg3:
	v_add_u32_e32 v249, 0x2000, v247
	global_load_dwordx4 v[154:157], v249, s[46:47]
	global_load_dwordx4 v[158:161], v249, s[46:47] offset:1024
	global_load_dwordx4 v[162:165], v249, s[46:47] offset:2048
	global_load_dwordx4 v[166:169], v249, s[46:47] offset:3072
	v_mbcnt_lo_u32_b32 v170, -1, 0
	v_mbcnt_hi_u32_b32 v170, -1, v170
	v_xor_b32_e32 v171, 16, v170
	v_xor_b32_e32 v172, 32, v170
	v_lshlrev_b32_e32 v171, 2, v171
	v_lshlrev_b32_e32 v172, 2, v172
	v_lshl_or_b32 v173, s59, 7, v148
	v_lshlrev_b32_e32 v173, 1, v173
	v_mad_u32_u24 v248, v246, s51, v173
	s_waitcnt vmcnt(12)
	v_add_f32_e32 v230, v230, v231
	v_add_f32_e32 v232, v232, v233
	v_add_f32_e32 v234, v234, v235
	v_add_f32_e32 v236, v236, v237
	v_add_f32_e32 v238, v238, v239
	v_add_f32_e32 v240, v240, v241
	v_add_f32_e32 v242, v242, v243
	v_add_f32_e32 v244, v244, v245
	v_add_f32_e32 v230, v230, v232
	v_add_f32_e32 v234, v234, v236
	v_add_f32_e32 v238, v238, v240
	v_add_f32_e32 v242, v242, v244
	ds_bpermute_b32 v231, v171, v230
	ds_bpermute_b32 v235, v171, v234
	ds_bpermute_b32 v239, v171, v238
	ds_bpermute_b32 v243, v171, v242
	s_waitcnt lgkmcnt(0)
	v_add_f32_e32 v230, v230, v231
	v_add_f32_e32 v234, v234, v235
	v_add_f32_e32 v238, v238, v239
	v_add_f32_e32 v242, v242, v243
	ds_bpermute_b32 v231, v172, v230
	ds_bpermute_b32 v235, v172, v234
	ds_bpermute_b32 v239, v172, v238
	ds_bpermute_b32 v243, v172, v242
	s_waitcnt lgkmcnt(0)
	v_add_f32_e32 v230, v230, v231
	v_add_f32_e32 v234, v234, v235
	v_add_f32_e32 v238, v238, v239
	v_add_f32_e32 v242, v242, v243
	v_fmamk_f32 v231, v230, 0x3a800000, v152
	v_fmamk_f32 v235, v234, 0x3a800000, v152
	v_fmamk_f32 v239, v238, 0x3a800000, v152
	v_fmamk_f32 v243, v242, 0x3a800000, v152
	v_rsq_f32_e32 v230, v231
	v_rsq_f32_e32 v234, v235
	v_rsq_f32_e32 v238, v239
	v_rsq_f32_e32 v242, v243
	s_nop 0
	v_mul_f32_e32 v230, 0xbfb8aa3b, v230
	v_mul_f32_e32 v234, 0xbfb8aa3b, v234
	v_mul_f32_e32 v238, 0xbfb8aa3b, v238
	v_mul_f32_e32 v242, 0xbfb8aa3b, v242
	v_mul_f32_e32 v176, v116, v230
	v_mul_f32_e32 v177, v117, v230
	v_mul_f32_e32 v178, v118, v230
	v_mul_f32_e32 v179, v119, v230
	v_mul_f32_e32 v180, v112, v230
	v_mul_f32_e32 v181, v113, v230
	v_mul_f32_e32 v182, v114, v230
	v_mul_f32_e32 v183, v115, v230
	v_exp_f32_e32 v176, v176
	v_exp_f32_e32 v177, v177
	v_exp_f32_e32 v178, v178
	v_exp_f32_e32 v179, v179
	v_exp_f32_e32 v180, v180
	v_exp_f32_e32 v181, v181
	v_exp_f32_e32 v182, v182
	v_exp_f32_e32 v183, v183
	v_fma_f32 v176, v176, v231, v231
	v_fma_f32 v177, v177, v231, v231
	v_fma_f32 v178, v178, v231, v231
	v_fma_f32 v179, v179, v231, v231
	v_fma_f32 v180, v180, v231, v231
	v_fma_f32 v181, v181, v231, v231
	v_fma_f32 v182, v182, v231, v231
	v_fma_f32 v183, v183, v231, v231
	v_rcp_f32_e32 v176, v176
	v_rcp_f32_e32 v177, v177
	v_rcp_f32_e32 v178, v178
	v_rcp_f32_e32 v179, v179
	v_rcp_f32_e32 v180, v180
	v_rcp_f32_e32 v181, v181
	v_rcp_f32_e32 v182, v182
	v_rcp_f32_e32 v183, v183
	v_pk_mul_f32 v[116:117], v[116:117], v[124:125]
	v_pk_mul_f32 v[118:119], v[118:119], v[126:127]
	v_pk_mul_f32 v[112:113], v[112:113], v[120:121]
	v_pk_mul_f32 v[114:115], v[114:115], v[122:123]
	v_pk_mul_f32 v[176:177], v[116:117], v[176:177]
	v_pk_mul_f32 v[178:179], v[118:119], v[178:179]
	v_pk_mul_f32 v[180:181], v[112:113], v[180:181]
	v_pk_mul_f32 v[182:183], v[114:115], v[182:183]
	v_cvt_pk_bf16_f32 v192, v176, v177
	v_cvt_pk_bf16_f32 v193, v178, v179
	v_cvt_pk_bf16_f32 v194, v180, v181
	v_cvt_pk_bf16_f32 v195, v182, v183
	v_mov_b32_e32 v200, v248
	global_store_dwordx4 v200, v[192:195], s[48:49] sc0 sc1
	v_mul_f32_e32 v184, v100, v234
	v_mul_f32_e32 v185, v101, v234
	v_mul_f32_e32 v186, v102, v234
	v_mul_f32_e32 v187, v103, v234
	v_mul_f32_e32 v188, v96, v234
	v_mul_f32_e32 v189, v97, v234
	v_mul_f32_e32 v190, v98, v234
	v_mul_f32_e32 v191, v99, v234
	v_exp_f32_e32 v184, v184
	v_exp_f32_e32 v185, v185
	v_exp_f32_e32 v186, v186
	v_exp_f32_e32 v187, v187
	v_exp_f32_e32 v188, v188
	v_exp_f32_e32 v189, v189
	v_exp_f32_e32 v190, v190
	v_exp_f32_e32 v191, v191
	v_fma_f32 v184, v184, v235, v235
	v_fma_f32 v185, v185, v235, v235
	v_fma_f32 v186, v186, v235, v235
	v_fma_f32 v187, v187, v235, v235
	v_fma_f32 v188, v188, v235, v235
	v_fma_f32 v189, v189, v235, v235
	v_fma_f32 v190, v190, v235, v235
	v_fma_f32 v191, v191, v235, v235
	v_rcp_f32_e32 v184, v184
	v_rcp_f32_e32 v185, v185
	v_rcp_f32_e32 v186, v186
	v_rcp_f32_e32 v187, v187
	v_rcp_f32_e32 v188, v188
	v_rcp_f32_e32 v189, v189
	v_rcp_f32_e32 v190, v190
	v_rcp_f32_e32 v191, v191
	v_pk_mul_f32 v[100:101], v[100:101], v[108:109]
	v_pk_mul_f32 v[102:103], v[102:103], v[110:111]
	v_pk_mul_f32 v[96:97], v[96:97], v[104:105]
	v_pk_mul_f32 v[98:99], v[98:99], v[106:107]
	v_pk_mul_f32 v[184:185], v[100:101], v[184:185]
	v_pk_mul_f32 v[186:187], v[102:103], v[186:187]
	v_pk_mul_f32 v[188:189], v[96:97], v[188:189]
	v_pk_mul_f32 v[190:191], v[98:99], v[190:191]
	v_cvt_pk_bf16_f32 v196, v184, v185
	v_cvt_pk_bf16_f32 v197, v186, v187
	v_cvt_pk_bf16_f32 v198, v188, v189
	v_cvt_pk_bf16_f32 v199, v190, v191
	v_add_u32_e32 v201, 0x16000, v248
	global_store_dwordx4 v201, v[196:199], s[48:49] sc0 sc1
	v_mul_f32_e32 v176, v84, v238
	v_mul_f32_e32 v177, v85, v238
	v_mul_f32_e32 v178, v86, v238
	v_mul_f32_e32 v179, v87, v238
	v_mul_f32_e32 v180, v80, v238
	v_mul_f32_e32 v181, v81, v238
	v_mul_f32_e32 v182, v82, v238
	v_mul_f32_e32 v183, v83, v238
	v_exp_f32_e32 v176, v176
	v_exp_f32_e32 v177, v177
	v_exp_f32_e32 v178, v178
	v_exp_f32_e32 v179, v179
	v_exp_f32_e32 v180, v180
	v_exp_f32_e32 v181, v181
	v_exp_f32_e32 v182, v182
	v_exp_f32_e32 v183, v183
	v_fma_f32 v176, v176, v239, v239
	v_fma_f32 v177, v177, v239, v239
;     __device__ __forceinline__ void operator()(AccRef acc, const pg8::Unit& u, int wr, int wc, int fr, int fq) const {
;         const int row0 = u.pm * 256 + wr * 64 + fr, col0 = u.pn * 128 + wc * 32 + 8 * fq;
; #pragma unroll
;         for (int ai = 0; ai < 2; ++ai)
; #pragma unroll
;             for (int m = 0; m < 4; ++m) {
;                 const int row = row0 + ai * 128 + m * 16;
;                 const float rs = rs_from(ssp + (size_t)row * 16, 4, 1.0f / 1024.0f);
;                 f32x4 o[2];
; #pragma unroll
;                 for (int n = 0; n < 2; ++n)
; #pragma unroll
;                     for (int j = 0; j < 4; ++j) {
;                         const float g = acc[ai][0][m][n][j] * rs, up = acc[ai][1][m][n][j] * rs;
;                         o[n][j] = g * __builtin_amdgcn_rcpf(1.0f + __expf(-g)) * up;
;                     }
;                 *(u32x4*)(act + (size_t)row * FF + col0) = pack8(o[0], o[1]);
	v_fma_f32 v178, v178, v239, v239
	v_fma_f32 v179, v179, v239, v239
	v_fma_f32 v180, v180, v239, v239
	v_fma_f32 v181, v181, v239, v239
	v_fma_f32 v182, v182, v239, v239
	v_fma_f32 v183, v183, v239, v239
	v_rcp_f32_e32 v176, v176
	v_rcp_f32_e32 v177, v177
	v_rcp_f32_e32 v178, v178
	v_rcp_f32_e32 v179, v179
	v_rcp_f32_e32 v180, v180
	v_rcp_f32_e32 v181, v181
	v_rcp_f32_e32 v182, v182
	v_rcp_f32_e32 v183, v183
	v_pk_mul_f32 v[84:85], v[84:85], v[92:93]
	v_pk_mul_f32 v[86:87], v[86:87], v[94:95]
	v_pk_mul_f32 v[80:81], v[80:81], v[88:89]
	v_pk_mul_f32 v[82:83], v[82:83], v[90:91]
	v_pk_mul_f32 v[176:177], v[84:85], v[176:177]
	v_pk_mul_f32 v[178:179], v[86:87], v[178:179]
	v_pk_mul_f32 v[180:181], v[80:81], v[180:181]
	v_pk_mul_f32 v[182:183], v[82:83], v[182:183]
	v_cvt_pk_bf16_f32 v192, v176, v177
	v_cvt_pk_bf16_f32 v193, v178, v179
	v_cvt_pk_bf16_f32 v194, v180, v181
	v_cvt_pk_bf16_f32 v195, v182, v183
	v_add_u32_e32 v200, 0x2c000, v248
	global_store_dwordx4 v200, v[192:195], s[48:49] sc0 sc1
	v_mul_f32_e32 v184, v68, v242
	v_mul_f32_e32 v185, v69, v242
	v_mul_f32_e32 v186, v70, v242
	v_mul_f32_e32 v187, v71, v242
	v_mul_f32_e32 v188, v64, v242
	v_mul_f32_e32 v189, v65, v242
	v_mul_f32_e32 v190, v66, v242
	v_mul_f32_e32 v191, v67, v242
	v_exp_f32_e32 v184, v184
	v_exp_f32_e32 v185, v185
	v_exp_f32_e32 v186, v186
	v_exp_f32_e32 v187, v187
	v_exp_f32_e32 v188, v188
	v_exp_f32_e32 v189, v189
	v_exp_f32_e32 v190, v190
	v_exp_f32_e32 v191, v191
	v_fma_f32 v184, v184, v243, v243
	v_fma_f32 v185, v185, v243, v243
	v_fma_f32 v186, v186, v243, v243
	v_fma_f32 v187, v187, v243, v243
	v_fma_f32 v188, v188, v243, v243
	v_fma_f32 v189, v189, v243, v243
	v_fma_f32 v190, v190, v243, v243
	v_fma_f32 v191, v191, v243, v243
	v_rcp_f32_e32 v184, v184
	v_rcp_f32_e32 v185, v185
	v_rcp_f32_e32 v186, v186
	v_rcp_f32_e32 v187, v187
	v_rcp_f32_e32 v188, v188
	v_rcp_f32_e32 v189, v189
	v_rcp_f32_e32 v190, v190
	v_rcp_f32_e32 v191, v191
	v_pk_mul_f32 v[68:69], v[68:69], v[76:77]
	v_pk_mul_f32 v[70:71], v[70:71], v[78:79]
	v_pk_mul_f32 v[64:65], v[64:65], v[72:73]
	v_pk_mul_f32 v[66:67], v[66:67], v[74:75]
	v_pk_mul_f32 v[184:185], v[68:69], v[184:185]
	v_pk_mul_f32 v[186:187], v[70:71], v[186:187]
	v_pk_mul_f32 v[188:189], v[64:65], v[188:189]
	v_pk_mul_f32 v[190:191], v[66:67], v[190:191]
	v_cvt_pk_bf16_f32 v196, v184, v185
	v_cvt_pk_bf16_f32 v197, v186, v187
	v_cvt_pk_bf16_f32 v198, v188, v189
	v_cvt_pk_bf16_f32 v199, v190, v191
	v_add_u32_e32 v201, 0x42000, v248
	global_store_dwordx4 v201, v[196:199], s[48:49] sc0 sc1
	s_waitcnt vmcnt(4)
	v_add_f32_e32 v154, v154, v155
	v_add_f32_e32 v156, v156, v157
	v_add_f32_e32 v158, v158, v159
	v_add_f32_e32 v160, v160, v161
	v_add_f32_e32 v162, v162, v163
	v_add_f32_e32 v164, v164, v165
	v_add_f32_e32 v166, v166, v167
	v_add_f32_e32 v168, v168, v169
	v_add_f32_e32 v154, v154, v156
	v_add_f32_e32 v158, v158, v160
	v_add_f32_e32 v162, v162, v164
	v_add_f32_e32 v166, v166, v168
	ds_bpermute_b32 v155, v171, v154
	ds_bpermute_b32 v159, v171, v158
	ds_bpermute_b32 v163, v171, v162
	ds_bpermute_b32 v167, v171, v166
	s_waitcnt lgkmcnt(0)
	v_add_f32_e32 v154, v154, v155
	v_add_f32_e32 v158, v158, v159
	v_add_f32_e32 v162, v162, v163
	v_add_f32_e32 v166, v166, v167
	ds_bpermute_b32 v155, v172, v154
	ds_bpermute_b32 v159, v172, v158
	ds_bpermute_b32 v163, v172, v162
	ds_bpermute_b32 v167, v172, v166
	s_waitcnt lgkmcnt(0)
; __device__ __forceinline__ float rs_from(const float* p, int n4, float inv_n) {
;     float s = 0.f;
;     for (int i = 0; i < n4; ++i) { const f32x4 v = *(const f32x4*)(p + 4 * i); s += (v[0] + v[1]) + (v[2] + v[3]); }
;     return rsqrtf(s * inv_n + EPS);
; }
;     __device__ __forceinline__ void operator()(AccRef acc, const pg8::Unit& u, int wr, int wc, int fr, int fq) const {
;         const int row0 = u.pm * 256 + wr * 64 + fr, col0 = u.pn * 128 + wc * 32 + 8 * fq;
; #pragma unroll
;         for (int ai = 0; ai < 2; ++ai)
; #pragma unroll
;             for (int m = 0; m < 4; ++m) {
;                 const int row = row0 + ai * 128 + m * 16;
;                 const float rs = rs_from(ssp + (size_t)row * 16, 4, 1.0f / 1024.0f);
;                 f32x4 o[2];
; #pragma unroll
;                 for (int n = 0; n < 2; ++n)
; #pragma unroll
;                     for (int j = 0; j < 4; ++j) {
;                         const float g = acc[ai][0][m][n][j] * rs, up = acc[ai][1][m][n][j] * rs;
;                         o[n][j] = g * __builtin_amdgcn_rcpf(1.0f + __expf(-g)) * up;
;                     }
;                 *(u32x4*)(act + (size_t)row * FF + col0) = pack8(o[0], o[1]);
	v_add_f32_e32 v154, v154, v155
	v_add_f32_e32 v158, v158, v159
	v_add_f32_e32 v162, v162, v163
	v_add_f32_e32 v166, v166, v167
	v_fmamk_f32 v155, v154, 0x3a800000, v152
	v_fmamk_f32 v159, v158, 0x3a800000, v152
	v_fmamk_f32 v163, v162, 0x3a800000, v152
	v_fmamk_f32 v167, v166, 0x3a800000, v152
	v_rsq_f32_e32 v154, v155
	v_rsq_f32_e32 v158, v159
	v_rsq_f32_e32 v162, v163
	v_rsq_f32_e32 v166, v167
	s_nop 0
	v_mul_f32_e32 v154, 0xbfb8aa3b, v154
	v_mul_f32_e32 v158, 0xbfb8aa3b, v158
	v_mul_f32_e32 v162, 0xbfb8aa3b, v162
	v_mul_f32_e32 v166, 0xbfb8aa3b, v166
	v_mul_f32_e32 v176, v52, v154
	v_mul_f32_e32 v177, v53, v154
	v_mul_f32_e32 v178, v54, v154
	v_mul_f32_e32 v179, v55, v154
	v_mul_f32_e32 v180, v48, v154
	v_mul_f32_e32 v181, v49, v154
	v_mul_f32_e32 v182, v50, v154
	v_mul_f32_e32 v183, v51, v154
	v_exp_f32_e32 v176, v176
	v_exp_f32_e32 v177, v177
	v_exp_f32_e32 v178, v178
	v_exp_f32_e32 v179, v179
	v_exp_f32_e32 v180, v180
	v_exp_f32_e32 v181, v181
	v_exp_f32_e32 v182, v182
	v_exp_f32_e32 v183, v183
	v_fma_f32 v176, v176, v155, v155
	v_fma_f32 v177, v177, v155, v155
	v_fma_f32 v178, v178, v155, v155
	v_fma_f32 v179, v179, v155, v155
	v_fma_f32 v180, v180, v155, v155
	v_fma_f32 v181, v181, v155, v155
	v_fma_f32 v182, v182, v155, v155
	v_fma_f32 v183, v183, v155, v155
	v_rcp_f32_e32 v176, v176
	v_rcp_f32_e32 v177, v177
	v_rcp_f32_e32 v178, v178
	v_rcp_f32_e32 v179, v179
	v_rcp_f32_e32 v180, v180
	v_rcp_f32_e32 v181, v181
	v_rcp_f32_e32 v182, v182
	v_rcp_f32_e32 v183, v183
	v_pk_mul_f32 v[52:53], v[52:53], v[60:61]
	v_pk_mul_f32 v[54:55], v[54:55], v[62:63]
	v_pk_mul_f32 v[48:49], v[48:49], v[56:57]
	v_pk_mul_f32 v[50:51], v[50:51], v[58:59]
	v_pk_mul_f32 v[176:177], v[52:53], v[176:177]
	v_pk_mul_f32 v[178:179], v[54:55], v[178:179]
	v_pk_mul_f32 v[180:181], v[48:49], v[180:181]
	v_pk_mul_f32 v[182:183], v[50:51], v[182:183]
	v_cvt_pk_bf16_f32 v192, v176, v177
	v_cvt_pk_bf16_f32 v193, v178, v179
	v_cvt_pk_bf16_f32 v194, v180, v181
	v_cvt_pk_bf16_f32 v195, v182, v183
	v_add_u32_e32 v200, 0xb0000, v248
	global_store_dwordx4 v200, v[192:195], s[48:49] sc0 sc1
	v_mul_f32_e32 v184, v36, v158
	v_mul_f32_e32 v185, v37, v158
	v_mul_f32_e32 v186, v38, v158
	v_mul_f32_e32 v187, v39, v158
	v_mul_f32_e32 v188, v32, v158
	v_mul_f32_e32 v189, v33, v158
	v_mul_f32_e32 v190, v34, v158
	v_mul_f32_e32 v191, v35, v158
	v_exp_f32_e32 v184, v184
	v_exp_f32_e32 v185, v185
	v_exp_f32_e32 v186, v186
	v_exp_f32_e32 v187, v187
	v_exp_f32_e32 v188, v188
	v_exp_f32_e32 v189, v189
	v_exp_f32_e32 v190, v190
	v_exp_f32_e32 v191, v191
	v_fma_f32 v184, v184, v159, v159
	v_fma_f32 v185, v185, v159, v159
	v_fma_f32 v186, v186, v159, v159
	v_fma_f32 v187, v187, v159, v159
	v_fma_f32 v188, v188, v159, v159
	v_fma_f32 v189, v189, v159, v159
	v_fma_f32 v190, v190, v159, v159
	v_fma_f32 v191, v191, v159, v159
	v_rcp_f32_e32 v184, v184
	v_rcp_f32_e32 v185, v185
	v_rcp_f32_e32 v186, v186
	v_rcp_f32_e32 v187, v187
	v_rcp_f32_e32 v188, v188
	v_rcp_f32_e32 v189, v189
	v_rcp_f32_e32 v190, v190
	v_rcp_f32_e32 v191, v191
	v_pk_mul_f32 v[36:37], v[36:37], v[44:45]
	v_pk_mul_f32 v[38:39], v[38:39], v[46:47]
	v_pk_mul_f32 v[32:33], v[32:33], v[40:41]
	v_pk_mul_f32 v[34:35], v[34:35], v[42:43]
	v_pk_mul_f32 v[184:185], v[36:37], v[184:185]
	v_pk_mul_f32 v[186:187], v[38:39], v[186:187]
	v_pk_mul_f32 v[188:189], v[32:33], v[188:189]
	v_pk_mul_f32 v[190:191], v[34:35], v[190:191]
	v_cvt_pk_bf16_f32 v196, v184, v185
	v_cvt_pk_bf16_f32 v197, v186, v187
	v_cvt_pk_bf16_f32 v198, v188, v189
	v_cvt_pk_bf16_f32 v199, v190, v191
	v_add_u32_e32 v201, 0xc6000, v248
	global_store_dwordx4 v201, v[196:199], s[48:49] sc0 sc1
	v_mul_f32_e32 v176, v20, v162
	v_mul_f32_e32 v177, v21, v162
	v_mul_f32_e32 v178, v22, v162
	v_mul_f32_e32 v179, v23, v162
	v_mul_f32_e32 v180, v16, v162
	v_mul_f32_e32 v181, v17, v162
	v_mul_f32_e32 v182, v18, v162
	v_mul_f32_e32 v183, v19, v162
	v_exp_f32_e32 v176, v176
	v_exp_f32_e32 v177, v177
	v_exp_f32_e32 v178, v178
	v_exp_f32_e32 v179, v179
	v_exp_f32_e32 v180, v180
	v_exp_f32_e32 v181, v181
	v_exp_f32_e32 v182, v182
	v_exp_f32_e32 v183, v183
	v_fma_f32 v176, v176, v163, v163
	v_fma_f32 v177, v177, v163, v163
	v_fma_f32 v178, v178, v163, v163
	v_fma_f32 v179, v179, v163, v163
	v_fma_f32 v180, v180, v163, v163
	v_fma_f32 v181, v181, v163, v163
	v_fma_f32 v182, v182, v163, v163
	v_fma_f32 v183, v183, v163, v163
	v_rcp_f32_e32 v176, v176
	v_rcp_f32_e32 v177, v177
	v_rcp_f32_e32 v178, v178
	v_rcp_f32_e32 v179, v179
	v_rcp_f32_e32 v180, v180
	v_rcp_f32_e32 v181, v181
	v_rcp_f32_e32 v182, v182
	v_rcp_f32_e32 v183, v183
	v_pk_mul_f32 v[20:21], v[20:21], v[28:29]
	v_pk_mul_f32 v[22:23], v[22:23], v[30:31]
	v_pk_mul_f32 v[16:17], v[16:17], v[24:25]
	v_pk_mul_f32 v[18:19], v[18:19], v[26:27]
	v_pk_mul_f32 v[176:177], v[20:21], v[176:177]
	v_pk_mul_f32 v[178:179], v[22:23], v[178:179]
	v_pk_mul_f32 v[180:181], v[16:17], v[180:181]
	v_pk_mul_f32 v[182:183], v[18:19], v[182:183]
	v_cvt_pk_bf16_f32 v192, v176, v177
	v_cvt_pk_bf16_f32 v193, v178, v179
	v_cvt_pk_bf16_f32 v194, v180, v181
	v_cvt_pk_bf16_f32 v195, v182, v183
	v_add_u32_e32 v200, 0xdc000, v248
	global_store_dwordx4 v200, v[192:195], s[48:49] sc0 sc1
	v_mul_f32_e32 v184, v4, v166
	v_mul_f32_e32 v185, v5, v166
	v_mul_f32_e32 v186, v6, v166
	v_mul_f32_e32 v187, v7, v166
	v_mul_f32_e32 v188, v0, v166
	v_mul_f32_e32 v189, v1, v166
	v_mul_f32_e32 v190, v2, v166
	v_mul_f32_e32 v191, v3, v166
	v_exp_f32_e32 v184, v184
	v_exp_f32_e32 v185, v185
	v_exp_f32_e32 v186, v186
	v_exp_f32_e32 v187, v187
	v_exp_f32_e32 v188, v188
	v_exp_f32_e32 v189, v189
	v_exp_f32_e32 v190, v190
	v_exp_f32_e32 v191, v191
	v_fma_f32 v184, v184, v167, v167
	v_fma_f32 v185, v185, v167, v167
	v_fma_f32 v186, v186, v167, v167
	v_fma_f32 v187, v187, v167, v167
	v_fma_f32 v188, v188, v167, v167
	v_fma_f32 v189, v189, v167, v167
	v_fma_f32 v190, v190, v167, v167
	v_fma_f32 v191, v191, v167, v167
	v_rcp_f32_e32 v184, v184
	v_rcp_f32_e32 v185, v185
	v_rcp_f32_e32 v186, v186
	v_rcp_f32_e32 v187, v187
	v_rcp_f32_e32 v188, v188
	v_rcp_f32_e32 v189, v189
	v_rcp_f32_e32 v190, v190
	v_rcp_f32_e32 v191, v191
	v_pk_mul_f32 v[4:5], v[4:5], v[12:13]
	v_pk_mul_f32 v[6:7], v[6:7], v[14:15]
	v_pk_mul_f32 v[0:1], v[0:1], v[8:9]
	v_pk_mul_f32 v[2:3], v[2:3], v[10:11]
	v_pk_mul_f32 v[184:185], v[4:5], v[184:185]
	v_pk_mul_f32 v[186:187], v[6:7], v[186:187]
	v_pk_mul_f32 v[188:189], v[0:1], v[188:189]
	v_pk_mul_f32 v[190:191], v[2:3], v[190:191]
	v_cvt_pk_bf16_f32 v196, v184, v185
	v_cvt_pk_bf16_f32 v197, v186, v187
	v_cvt_pk_bf16_f32 v198, v188, v189
	v_cvt_pk_bf16_f32 v199, v190, v191
	v_add_u32_e32 v201, 0xf2000, v248
	global_store_dwordx4 v201, v[196:199], s[48:49] sc0 sc1
